# S5 pass1/pass3 loops: all LDS fragment reads issued up front into distinct buffers with counted lgkmcnt (was read-wait-mfma serialized)
# speedup vs baseline: 1.1469x; 1.0010x over previous
.LBB0_445:
	ds_read_b128 v[128:131], v34
	ds_read_b128 v[132:135], v34 offset:64
	ds_read_b128 v[136:139], v34 offset:128
	ds_read_b128 v[140:143], v34 offset:192
	ds_read_b128 v[144:147], v34 offset:256
	ds_read_b128 v[148:151], v34 offset:320
	ds_read_b128 v[152:155], v34 offset:384
	ds_read_b128 v[156:159], v34 offset:448
	s_add_i32 s0, s0, -1
	s_waitcnt lgkmcnt(7)
	v_mfma_f32_16x16x32_bf16 v[36:39], v[128:131], v[0:3], 0
	s_waitcnt lgkmcnt(6)
	v_mfma_f32_16x16x32_bf16 v[36:39], v[132:135], v[4:7], v[36:39]
	s_waitcnt lgkmcnt(5)
	v_mfma_f32_16x16x32_bf16 v[36:39], v[136:139], v[8:11], v[36:39]
	s_waitcnt lgkmcnt(4)
	v_mfma_f32_16x16x32_bf16 v[36:39], v[140:143], v[12:15], v[36:39]
	s_waitcnt lgkmcnt(3)
	v_mfma_f32_16x16x32_bf16 v[36:39], v[144:147], v[16:19], v[36:39]
	s_waitcnt lgkmcnt(2)
	v_mfma_f32_16x16x32_bf16 v[36:39], v[148:151], v[20:23], v[36:39]
	s_waitcnt lgkmcnt(1)
	v_mfma_f32_16x16x32_bf16 v[36:39], v[152:155], v[24:27], v[36:39]
	s_waitcnt lgkmcnt(0)
	v_mfma_f32_16x16x32_bf16 v[36:39], v[156:159], v[28:31], v[36:39]
	v_add_u32_e32 v40, 0x10a10, v33
	v_add_u32_e32 v41, 0x10c10, v33
	v_add_u32_e32 v42, 0x10e10, v33
	v_add_u32_e32 v35, 0x11010, v33
	v_add_u32_e32 v34, 0x2100, v34
	v_add_u32_e32 v33, 0x2000, v33
	s_nop 1
	ds_write_b32 v40, v36
	ds_write_b32 v41, v37
	ds_write_b32 v42, v38
	ds_write_b32 v35, v39
	s_cmp_eq_u32 s0, 0
	s_cbranch_scc0 .LBB0_445
	s_ashr_i32 s0, s7, 5
	s_mul_i32 s1, s30, 0x30000
	s_add_u32 s18, s76, s1
	s_addc_u32 s19, s77, 0
	v_lshlrev_b32_e32 v0, 1, v32
	v_mov_b32_e32 v1, v105
	v_lshl_or_b32 v50, v112, 5, v109
	v_lshl_add_u64 v[48:49], s[18:19], 0, v[0:1]
	v_mad_i64_i32 v[44:45], s[18:19], v50, s5, v[48:49]
	v_or_b32_e32 v50, 16, v50
	v_mad_i64_i32 v[92:93], s[18:19], v50, s5, v[48:49]
	s_waitcnt lgkmcnt(0)
	s_barrier
	global_load_dwordx4 v[0:3], v[44:45], off
	global_load_dwordx4 v[4:7], v[44:45], off offset:64
	global_load_dwordx4 v[8:11], v[44:45], off offset:128
	global_load_dwordx4 v[12:15], v[44:45], off offset:192
	global_load_dwordx4 v[16:19], v[44:45], off offset:256
	global_load_dwordx4 v[20:23], v[44:45], off offset:320
	global_load_dwordx4 v[24:27], v[44:45], off offset:384
	global_load_dwordx4 v[28:31], v[44:45], off offset:448
	global_load_dwordx4 v[32:35], v[44:45], off offset:512
	global_load_dwordx4 v[36:39], v[44:45], off offset:576
	global_load_dwordx4 v[40:43], v[44:45], off offset:640
	s_nop 0
	global_load_dwordx4 v[44:47], v[44:45], off offset:704
	s_nop 0
	global_load_dwordx4 v[48:51], v[92:93], off
	global_load_dwordx4 v[52:55], v[92:93], off offset:64
	global_load_dwordx4 v[56:59], v[92:93], off offset:128
	global_load_dwordx4 v[60:63], v[92:93], off offset:192
	global_load_dwordx4 v[64:67], v[92:93], off offset:256
	global_load_dwordx4 v[68:71], v[92:93], off offset:320
	global_load_dwordx4 v[72:75], v[92:93], off offset:384
	global_load_dwordx4 v[76:79], v[92:93], off offset:448
	global_load_dwordx4 v[80:83], v[92:93], off offset:512
	global_load_dwordx4 v[84:87], v[92:93], off offset:576
	global_load_dwordx4 v[88:91], v[92:93], off offset:640
	s_nop 0
	global_load_dwordx4 v[92:95], v[92:93], off offset:704
	v_cmp_gt_u32_e32 vcc, 64, v96
	s_and_saveexec_b64 s[18:19], vcc
	s_cbranch_execz .LBB0_464
	s_lshl_b32 s1, s30, 7
	v_readlane_b32 s34, v250, 41
	v_lshl_or_b32 v98, v96, 1, s1
	v_mov_b32_e32 v99, v105
	v_readlane_b32 s35, v250, 42
	v_lshlrev_b32_e32 v116, 1, v115
	v_lshlrev_b32_e32 v117, 2, v96
	v_lshl_add_u64 v[98:99], v[98:99], 2, s[34:35]
	global_load_dwordx2 v[98:99], v[98:99], off
	v_mov_b32_e32 v108, 0
	s_mov_b32 s1, -4
	v_mov_b32_e32 v96, 0
	s_waitcnt vmcnt(0)
	v_pk_mov_b32 v[100:101], v[98:99], v[98:99] op_sel:[1,0]
	v_add_u32_e32 v117, 0x10a10, v117
	v_add_u32_e32 v116, 0x10a10, v116
	v_mov_b32_e32 v96, 0
	v_mov_b32_e32 v97, 0
	ds_read_b32 v100, v117
	ds_read_b32 v101, v117 offset:256
	ds_read_b32 v102, v117 offset:512
	ds_read_b32 v103, v117 offset:768
	ds_read_b32 v106, v117 offset:1024
	ds_read_b32 v107, v117 offset:1280
	ds_read_b32 v110, v117 offset:1536
	ds_read_b32 v111, v117 offset:1792
	s_mov_b32 s1, 16
	s_waitcnt lgkmcnt(0)

.LBB0_466:
	v_add_u32_e32 v109, v113, v104
	v_add_u32_e32 v110, v112, v104
	v_add_u32_e32 v110, 0x10a10, v110
	ds_read_b128 v[128:131], v109
	ds_read_b128 v[132:135], v109 offset:64
	ds_read_b128 v[136:139], v109 offset:128
	ds_read_b128 v[140:143], v109 offset:192
	ds_read_b128 v[144:147], v109 offset:256
	ds_read_b128 v[148:151], v109 offset:320
	ds_read_b128 v[152:155], v109 offset:384
	ds_read_b128 v[156:159], v109 offset:448
	ds_read_b128 v[160:163], v110
	ds_read_b128 v[164:167], v110 offset:64
	ds_read_b128 v[168:171], v110 offset:128
	ds_read_b128 v[172:175], v110 offset:192
	v_add_u32_e32 v114, s18, v115
	v_cmp_gt_u32_e32 vcc, s6, v114
	s_waitcnt lgkmcnt(11)
	v_mfma_f32_16x16x32_bf16 v[100:103], v[128:131], v[0:3], 0
	v_mfma_f32_16x16x32_bf16 v[96:99], v[128:131], v[48:51], 0
	s_waitcnt lgkmcnt(10)
	v_mfma_f32_16x16x32_bf16 v[100:103], v[132:135], v[4:7], v[100:103]
	v_mfma_f32_16x16x32_bf16 v[96:99], v[132:135], v[52:55], v[96:99]
	s_waitcnt lgkmcnt(9)
	v_mfma_f32_16x16x32_bf16 v[100:103], v[136:139], v[8:11], v[100:103]
	v_mfma_f32_16x16x32_bf16 v[96:99], v[136:139], v[56:59], v[96:99]
	s_waitcnt lgkmcnt(8)
	v_mfma_f32_16x16x32_bf16 v[100:103], v[140:143], v[12:15], v[100:103]
	v_mfma_f32_16x16x32_bf16 v[96:99], v[140:143], v[60:63], v[96:99]
	s_waitcnt lgkmcnt(7)
	v_mfma_f32_16x16x32_bf16 v[100:103], v[144:147], v[16:19], v[100:103]
	v_mfma_f32_16x16x32_bf16 v[96:99], v[144:147], v[64:67], v[96:99]
	s_waitcnt lgkmcnt(6)
	v_mfma_f32_16x16x32_bf16 v[100:103], v[148:151], v[20:23], v[100:103]
	v_mfma_f32_16x16x32_bf16 v[96:99], v[148:151], v[68:71], v[96:99]
	s_waitcnt lgkmcnt(5)
	v_mfma_f32_16x16x32_bf16 v[100:103], v[152:155], v[24:27], v[100:103]
	v_mfma_f32_16x16x32_bf16 v[96:99], v[152:155], v[72:75], v[96:99]
	s_waitcnt lgkmcnt(4)
	v_mfma_f32_16x16x32_bf16 v[100:103], v[156:159], v[28:31], v[100:103]
	v_mfma_f32_16x16x32_bf16 v[96:99], v[156:159], v[76:79], v[96:99]
	s_waitcnt lgkmcnt(3)
	v_mfma_f32_16x16x32_bf16 v[100:103], v[160:163], v[32:35], v[100:103]
	v_mfma_f32_16x16x32_bf16 v[96:99], v[160:163], v[80:83], v[96:99]
	s_waitcnt lgkmcnt(2)
	v_mfma_f32_16x16x32_bf16 v[100:103], v[164:167], v[36:39], v[100:103]
	v_mfma_f32_16x16x32_bf16 v[96:99], v[164:167], v[84:87], v[96:99]
	s_waitcnt lgkmcnt(1)
	v_mfma_f32_16x16x32_bf16 v[100:103], v[168:171], v[40:43], v[100:103]
	v_mfma_f32_16x16x32_bf16 v[96:99], v[168:171], v[88:91], v[96:99]
	s_waitcnt lgkmcnt(0)
	v_mfma_f32_16x16x32_bf16 v[100:103], v[172:175], v[44:47], v[100:103]
	v_mfma_f32_16x16x32_bf16 v[96:99], v[172:175], v[92:95], v[96:99]
	v_ashrrev_i32_e32 v109, 31, v108
	v_lshlrev_b64 v[110:111], 10, v[108:109]
	v_lshl_add_u64 v[110:111], v[106:107], 0, v[110:111]
	s_and_saveexec_b64 s[0:1], vcc
	s_cbranch_execz .LBB0_468
	s_nop 3
	v_mul_f32_e32 v109, 0x3d372713, v100
	v_mul_f32_e32 v109, v100, v109
	v_fma_f32 v109, v100, v109, v100
	v_mul_f32_e32 v109, 0x3fcc422a, v109
	v_mul_f32_e32 v109, 0xbfb8aa3b, v109
	v_exp_f32_e32 v109, v109
	s_nop 0
	v_add_f32_e32 v109, 1.0, v109
	v_rcp_f32_e32 v109, v109
	s_nop 0
	v_mul_f32_e32 v100, v100, v109
	v_cvt_pk_bf16_f32 v100, v100, v105
	global_store_short v[110:111], v100, off
	v_mul_f32_e32 v100, 0x3d372713, v96
	v_mul_f32_e32 v100, v96, v100
	v_fma_f32 v100, v96, v100, v96
	v_mul_f32_e32 v100, 0x3fcc422a, v100
	v_mul_f32_e32 v100, 0xbfb8aa3b, v100
	v_exp_f32_e32 v100, v100
	s_nop 0
	v_add_f32_e32 v100, 1.0, v100
	v_rcp_f32_e32 v100, v100
	s_nop 0
	v_mul_f32_e32 v96, v96, v100
	v_cvt_pk_bf16_f32 v96, v96, v105
	global_store_short v[110:111], v96, off offset:1024
